# MLA loop: removed redundant self-max canonicalization (8 dependent VALU per iteration) from the lazy-rescale max chains; bit-identical output
# speedup vs baseline: 1.0070x; 1.0070x over previous
; DI int crow(int r, int hi) { return (r & 3) + 8 * (r >> 2) + 4 * hi; }
; DI f32x16 mfma(bf16x8 a, bf16x8 b, f32x16 c) { return __builtin_amdgcn_mfma_f32_32x32x16_bf16(a, b, c, 0, 0, 0); }
; DI float ex2(float x) { return __builtin_amdgcn_exp2f(x); }
; DI float xmax32(float v) { auto rr = __builtin_amdgcn_permlane32_swap(__float_as_uint(v), __float_as_uint(v), false, false); return fmaxf(__uint_as_float(rr[0]), __uint_as_float(rr[1])); }
; template <int DQK>
; DI void attn_unit(int tid, char* lds, const u16* Qp, const u16* K1, const u16* V1, int nt1, int kpos0, const u16* K2, const u16* V2, int nt2, int qpos0, bool mask, float m_init, float l_init, u16* Op) {
;     ...
;   auto qk = [&](int st, f32x16& p0, f32x16& p1) {
;     const char* Kb = lds + st * SB + kro;
; #pragma unroll
;     for (int d0 = 0; d0 < ND; ++d0) {
;       const bf16x8 a0 = *(const bf16x8*)(Kb + d0 * 32);
;       const bf16x8 a1 = *(const bf16x8*)(Kb + 32 * KP + d0 * 32);
;       if (d0 == 0) { p0 = mfma(a0, qr[0], negm); p1 = mfma(a1, qr[0], negm); } else { p0 = mfma(a0, qr[d0], p0); p1 = mfma(a1, qr[d0], p1); }
;     }
;   };
;   const int qw0 = qpos0 + wid * 32;
;   auto live = [&](int i) { if (!mask || i >= nt1) return true; const int kb = kpos0 + i * 64; return kb + 63 >= qw0 - 128 && kb <= qw0 + 31 + 128; };
;   auto step = [&](f32x16& c0, f32x16& c1, f32x16& n0, f32x16& n1, int i, int s_cur, int s_nxt, int s_wr) {
;     const bool has_nxt = i + 1 < NT, has_wr = i + 2 < NT;
;     if (has_wr) gl(i + 2);
;     if (has_nxt && live(i + 1)) qk(s_nxt, n0, n1);
;     if (live(i)) {
;     if (mask && i < nt1) {
;       const int kb = kpos0 + i * 64 - qpos;
; #pragma unroll
;       for (int r = 0; r < 16; ++r) {
;         const int d0_ = kb + crow(r, hi), d1_ = d0_ + 32;
;         if (d0_ > 128 || d0_ < -128) c0[r] = -1e30f;
;         if (d1_ > 128 || d1_ < -128) c1[r] = -1e30f;
;       }
;     }
;     float mt = c0[0];
; #pragma unroll
;     for (int r = 1; r < 16; ++r) mt = fmaxf(mt, c0[r]);
; #pragma unroll
;     for (int r = 0; r < 16; ++r) mt = fmaxf(mt, c1[r]);
;     mt = xmax32(mt);
;     if (__any(mt > THR)) {
;       const float delta = fmaxf(mt, 0.f), alpha = ex2(-delta);
;       mrun += delta; lrun *= alpha;
; #pragma unroll
;       for (int r = 0; r < 16; ++r) { o0[r] *= alpha; o1[r] *= alpha; c0[r] -= delta; c1[r] -= delta; n0[r] -= delta; n1[r] -= delta; negm[r] = -mrun; }
;     }
.LBB0_682:
	s_mul_i32 s25, s21, 0x5400
	v_add_u32_e32 v0, s25, v247
	ds_read_b128 v[114:117], v0 offset:6912
	ds_read_b128 v[98:101], v0 offset:256
	ds_read_b128 v[118:121], v0 offset:288
	s_waitcnt lgkmcnt(1)
	v_mfma_f32_32x32x16_bf16 v[82:97], v[98:101], v[162:165], v[34:49]
	v_mfma_f32_32x32x16_bf16 v[98:113], v[114:117], v[162:165], v[34:49]
	ds_read_b128 v[114:117], v0 offset:6944
	s_waitcnt lgkmcnt(0)
	v_mfma_f32_32x32x16_bf16 v[98:113], v[114:117], v[166:169], v[98:113]
	v_mfma_f32_32x32x16_bf16 v[82:97], v[118:121], v[166:169], v[82:97]
	ds_read_b128 v[114:117], v0 offset:6976
	ds_read_b128 v[118:121], v0 offset:320
	s_waitcnt lgkmcnt(1)
	v_mfma_f32_32x32x16_bf16 v[98:113], v[114:117], v[170:173], v[98:113]
	s_waitcnt lgkmcnt(0)
	v_mfma_f32_32x32x16_bf16 v[82:97], v[118:121], v[170:173], v[82:97]
	ds_read_b128 v[114:117], v0 offset:7008
	ds_read_b128 v[118:121], v0 offset:352
	s_waitcnt lgkmcnt(1)
	v_mfma_f32_32x32x16_bf16 v[98:113], v[114:117], v[174:177], v[98:113]
	s_waitcnt lgkmcnt(0)
	v_mfma_f32_32x32x16_bf16 v[82:97], v[118:121], v[174:177], v[82:97]
	ds_read_b128 v[114:117], v0 offset:7040
	ds_read_b128 v[118:121], v0 offset:384
	s_waitcnt lgkmcnt(1)
	v_mfma_f32_32x32x16_bf16 v[98:113], v[114:117], v[178:181], v[98:113]
	s_waitcnt lgkmcnt(0)
	v_mfma_f32_32x32x16_bf16 v[82:97], v[118:121], v[178:181], v[82:97]
	ds_read_b128 v[114:117], v0 offset:7072
	ds_read_b128 v[118:121], v0 offset:416
	s_waitcnt lgkmcnt(1)
	v_mfma_f32_32x32x16_bf16 v[98:113], v[114:117], v[182:185], v[98:113]
	v_max_f32_e32 v0, v50, v51
	v_max3_f32 v0, v0, v52, v53
	v_max3_f32 v0, v0, v54, v55
	v_max3_f32 v0, v0, v56, v57
	v_max3_f32 v0, v0, v58, v59
	v_max3_f32 v0, v0, v60, v61
	v_max3_f32 v0, v0, v62, v63
	v_max3_f32 v0, v0, v64, v65
	v_max3_f32 v0, v0, v66, v67
	v_max3_f32 v0, v0, v68, v69
	v_max3_f32 v0, v0, v70, v71
	v_max3_f32 v0, v0, v72, v73
	v_max3_f32 v0, v0, v74, v75
	s_waitcnt lgkmcnt(0)
	v_mfma_f32_32x32x16_bf16 v[82:97], v[118:121], v[182:185], v[82:97]
	v_max3_f32 v0, v0, v76, v77
	v_max3_f32 v0, v0, v78, v79
	v_max3_f32 v0, v0, v80, v81
	v_mov_b32_e32 v114, v0
	s_nop 1
	v_permlane32_swap_b32_e32 v0, v114
	v_max_f32_e32 v0, v0, v114
	v_cmp_lt_f32_e32 vcc, s2, v0
	s_cbranch_vccz .LBB0_684
	v_max_f32_e32 v0, v0, v0
	v_max_f32_e32 v0, 0, v0
	v_exp_f32_e64 v34, -v0
	v_add_f32_e32 v216, v216, v0
	v_xor_b32_e32 v114, 0x80000000, v216
	v_pk_add_f32 v[50:51], v[50:51], v[0:1] op_sel_hi:[1,0] neg_lo:[0,1] neg_hi:[0,1]
	v_mul_f32_e32 v215, v215, v34
	v_pk_add_f32 v[66:67], v[66:67], v[0:1] op_sel_hi:[1,0] neg_lo:[0,1] neg_hi:[0,1]
	v_pk_add_f32 v[52:53], v[52:53], v[0:1] op_sel_hi:[1,0] neg_lo:[0,1] neg_hi:[0,1]
	v_pk_add_f32 v[68:69], v[68:69], v[0:1] op_sel_hi:[1,0] neg_lo:[0,1] neg_hi:[0,1]
	v_pk_add_f32 v[54:55], v[54:55], v[0:1] op_sel_hi:[1,0] neg_lo:[0,1] neg_hi:[0,1]
	v_pk_add_f32 v[70:71], v[70:71], v[0:1] op_sel_hi:[1,0] neg_lo:[0,1] neg_hi:[0,1]
	v_pk_add_f32 v[56:57], v[56:57], v[0:1] op_sel_hi:[1,0] neg_lo:[0,1] neg_hi:[0,1]
	v_pk_add_f32 v[72:73], v[72:73], v[0:1] op_sel_hi:[1,0] neg_lo:[0,1] neg_hi:[0,1]
	v_pk_add_f32 v[58:59], v[58:59], v[0:1] op_sel_hi:[1,0] neg_lo:[0,1] neg_hi:[0,1]
	v_pk_add_f32 v[74:75], v[74:75], v[0:1] op_sel_hi:[1,0] neg_lo:[0,1] neg_hi:[0,1]
	v_pk_add_f32 v[60:61], v[60:61], v[0:1] op_sel_hi:[1,0] neg_lo:[0,1] neg_hi:[0,1]
	v_pk_add_f32 v[76:77], v[76:77], v[0:1] op_sel_hi:[1,0] neg_lo:[0,1] neg_hi:[0,1]
	v_pk_add_f32 v[62:63], v[62:63], v[0:1] op_sel_hi:[1,0] neg_lo:[0,1] neg_hi:[0,1]
	v_pk_add_f32 v[78:79], v[78:79], v[0:1] op_sel_hi:[1,0] neg_lo:[0,1] neg_hi:[0,1]
	v_pk_mul_f32 v[32:33], v[32:33], v[34:35] op_sel_hi:[1,0]
	v_pk_mul_f32 v[30:31], v[30:31], v[34:35] op_sel_hi:[1,0]
	v_pk_mul_f32 v[28:29], v[28:29], v[34:35] op_sel_hi:[1,0]
	v_pk_mul_f32 v[26:27], v[26:27], v[34:35] op_sel_hi:[1,0]
	v_pk_mul_f32 v[24:25], v[24:25], v[34:35] op_sel_hi:[1,0]
	v_pk_mul_f32 v[22:23], v[22:23], v[34:35] op_sel_hi:[1,0]
	v_pk_mul_f32 v[20:21], v[20:21], v[34:35] op_sel_hi:[1,0]
	v_pk_mul_f32 v[18:19], v[18:19], v[34:35] op_sel_hi:[1,0]
	v_pk_mul_f32 v[16:17], v[16:17], v[34:35] op_sel_hi:[1,0]
	v_pk_mul_f32 v[14:15], v[14:15], v[34:35] op_sel_hi:[1,0]
	v_pk_mul_f32 v[12:13], v[12:13], v[34:35] op_sel_hi:[1,0]
	v_pk_mul_f32 v[10:11], v[10:11], v[34:35] op_sel_hi:[1,0]
	v_pk_mul_f32 v[8:9], v[8:9], v[34:35] op_sel_hi:[1,0]
	v_pk_mul_f32 v[6:7], v[6:7], v[34:35] op_sel_hi:[1,0]
	v_pk_mul_f32 v[4:5], v[4:5], v[34:35] op_sel_hi:[1,0]
	v_pk_mul_f32 v[2:3], v[2:3], v[34:35] op_sel_hi:[1,0]
	v_pk_add_f32 v[64:65], v[64:65], v[0:1] op_sel_hi:[1,0] neg_lo:[0,1] neg_hi:[0,1]
	v_pk_add_f32 v[80:81], v[80:81], v[0:1] op_sel_hi:[1,0] neg_lo:[0,1] neg_hi:[0,1]
	v_sub_f32_e32 v97, v97, v0
	v_sub_f32_e32 v96, v96, v0
	v_sub_f32_e32 v95, v95, v0
	v_sub_f32_e32 v94, v94, v0
	v_sub_f32_e32 v93, v93, v0
	v_sub_f32_e32 v92, v92, v0
	v_sub_f32_e32 v91, v91, v0
	v_sub_f32_e32 v90, v90, v0
	v_sub_f32_e32 v89, v89, v0
	v_sub_f32_e32 v88, v88, v0
	v_sub_f32_e32 v87, v87, v0
	v_sub_f32_e32 v86, v86, v0
	v_sub_f32_e32 v85, v85, v0
	v_sub_f32_e32 v84, v84, v0
	v_sub_f32_e32 v83, v83, v0
	v_sub_f32_e32 v82, v82, v0
	v_sub_f32_e32 v113, v113, v0
	v_sub_f32_e32 v112, v112, v0
	v_sub_f32_e32 v111, v111, v0
	v_sub_f32_e32 v110, v110, v0
	v_sub_f32_e32 v109, v109, v0
	v_sub_f32_e32 v108, v108, v0
	v_sub_f32_e32 v107, v107, v0
	v_sub_f32_e32 v106, v106, v0
	v_sub_f32_e32 v105, v105, v0
	v_sub_f32_e32 v104, v104, v0
	v_sub_f32_e32 v103, v103, v0
	v_sub_f32_e32 v102, v102, v0
	v_sub_f32_e32 v101, v101, v0
	v_sub_f32_e32 v100, v100, v0
	v_sub_f32_e32 v99, v99, v0
	v_sub_f32_e32 v98, v98, v0
	v_mov_b32_e32 v115, v114
	v_mov_b32_e32 v116, v114
	v_mov_b32_e32 v117, v114
	v_mov_b32_e32 v118, v114
	v_mov_b32_e32 v119, v114
	v_mov_b32_e32 v120, v114
	v_mov_b32_e32 v121, v114
	v_mov_b32_e32 v122, v114
	v_mov_b32_e32 v123, v114
	v_mov_b32_e32 v124, v114
	v_mov_b32_e32 v125, v114
	v_mov_b32_e32 v126, v114
	v_mov_b32_e32 v127, v114
	v_mov_b32_e32 v128, v114
	v_mov_b32_e32 v129, v114
	v_mov_b32_e32 v34, v114
	v_mov_b32_e32 v35, v114
	v_mov_b32_e32 v36, v114
	v_mov_b32_e32 v37, v114
	v_mov_b32_e32 v38, v114
	v_mov_b32_e32 v39, v114
	v_mov_b32_e32 v40, v114
	v_mov_b32_e32 v41, v114
	v_mov_b32_e32 v42, v114
	v_mov_b32_e32 v43, v114
	v_mov_b32_e32 v44, v114
	v_mov_b32_e32 v45, v114
	v_mov_b32_e32 v46, v114
	v_mov_b32_e32 v47, v114
	v_mov_b32_e32 v48, v114
	v_mov_b32_e32 v49, v114
	s_branch .LBB0_685

; DI float ex2(float x) { return __builtin_amdgcn_exp2f(x); }
; DI float xmax32(float v) { auto rr = __builtin_amdgcn_permlane32_swap(__float_as_uint(v), __float_as_uint(v), false, false); return fmaxf(__uint_as_float(rr[0]), __uint_as_float(rr[1])); }
; template <int DQK>
; DI void attn_unit(int tid, char* lds, const u16* Qp, const u16* K1, const u16* V1, int nt1, int kpos0, const u16* K2, const u16* V2, int nt2, int qpos0, bool mask, float m_init, float l_init, u16* Op) {
;     ...
;     float mt = c0[0];
; #pragma unroll
;     for (int r = 1; r < 16; ++r) mt = fmaxf(mt, c0[r]);
; #pragma unroll
;     for (int r = 0; r < 16; ++r) mt = fmaxf(mt, c1[r]);
;     mt = xmax32(mt);
;     if (__any(mt > THR)) {
;       const float delta = fmaxf(mt, 0.f), alpha = ex2(-delta);
;       mrun += delta; lrun *= alpha;
; #pragma unroll
;       for (int r = 0; r < 16; ++r) { o0[r] *= alpha; o1[r] *= alpha; c0[r] -= delta; c1[r] -= delta; n0[r] -= delta; n1[r] -= delta; negm[r] = -mrun; }
;     }
;     float ls = 0.f;
; #pragma unroll
;     for (int r = 0; r < 16; ++r) { c0[r] = ex2(c0[r]); c1[r] = ex2(c1[r]); ls += c0[r] + c1[r]; }
;     lrun += ls;
.LBB0_694:
	v_add_f32_e32 v0, v126, v127
	v_max_f32_e32 v114, v82, v83
	v_max3_f32 v114, v114, v84, v85
	v_max3_f32 v114, v114, v86, v87
	v_max3_f32 v114, v114, v88, v89
	v_max3_f32 v114, v114, v90, v91
	v_max3_f32 v114, v114, v92, v93
	v_max3_f32 v114, v114, v94, v95
	v_max3_f32 v114, v114, v96, v97
	v_max3_f32 v114, v114, v98, v99
	v_max3_f32 v114, v114, v100, v101
	v_max3_f32 v114, v114, v102, v103
	v_max3_f32 v114, v114, v104, v105
	v_max3_f32 v114, v114, v106, v107
	v_max3_f32 v114, v114, v108, v109
	v_max3_f32 v114, v114, v110, v111
	v_max3_f32 v114, v114, v112, v113
	v_mov_b32_e32 v115, v114
	s_nop 1
	v_permlane32_swap_b32_e32 v114, v115
	v_max_f32_e32 v114, v114, v115
	v_add_f32_e32 v0, v215, v0
	v_cmp_lt_f32_e32 vcc, s2, v114
	s_cbranch_vccz .LBB0_696
	v_max_f32_e32 v34, v114, v114
	v_max_f32_e32 v36, 0, v34
	v_exp_f32_e64 v38, -v36
	v_add_f32_e32 v216, v216, v36
	v_xor_b32_e32 v34, 0x80000000, v216
	v_pk_add_f32 v[82:83], v[82:83], v[36:37] op_sel_hi:[1,0] neg_lo:[0,1] neg_hi:[0,1]
	v_mul_f32_e32 v0, v0, v38
	v_pk_add_f32 v[98:99], v[98:99], v[36:37] op_sel_hi:[1,0] neg_lo:[0,1] neg_hi:[0,1]
	v_pk_add_f32 v[84:85], v[84:85], v[36:37] op_sel_hi:[1,0] neg_lo:[0,1] neg_hi:[0,1]
	v_pk_add_f32 v[100:101], v[100:101], v[36:37] op_sel_hi:[1,0] neg_lo:[0,1] neg_hi:[0,1]
	v_pk_add_f32 v[86:87], v[86:87], v[36:37] op_sel_hi:[1,0] neg_lo:[0,1] neg_hi:[0,1]
	v_pk_add_f32 v[102:103], v[102:103], v[36:37] op_sel_hi:[1,0] neg_lo:[0,1] neg_hi:[0,1]
	v_pk_add_f32 v[88:89], v[88:89], v[36:37] op_sel_hi:[1,0] neg_lo:[0,1] neg_hi:[0,1]
	v_pk_add_f32 v[104:105], v[104:105], v[36:37] op_sel_hi:[1,0] neg_lo:[0,1] neg_hi:[0,1]
	v_pk_add_f32 v[90:91], v[90:91], v[36:37] op_sel_hi:[1,0] neg_lo:[0,1] neg_hi:[0,1]
	v_pk_add_f32 v[106:107], v[106:107], v[36:37] op_sel_hi:[1,0] neg_lo:[0,1] neg_hi:[0,1]
	v_pk_add_f32 v[92:93], v[92:93], v[36:37] op_sel_hi:[1,0] neg_lo:[0,1] neg_hi:[0,1]
	v_pk_add_f32 v[108:109], v[108:109], v[36:37] op_sel_hi:[1,0] neg_lo:[0,1] neg_hi:[0,1]
	v_pk_add_f32 v[94:95], v[94:95], v[36:37] op_sel_hi:[1,0] neg_lo:[0,1] neg_hi:[0,1]
	v_pk_add_f32 v[110:111], v[110:111], v[36:37] op_sel_hi:[1,0] neg_lo:[0,1] neg_hi:[0,1]
	v_pk_mul_f32 v[32:33], v[32:33], v[38:39] op_sel_hi:[1,0]
	v_pk_mul_f32 v[30:31], v[30:31], v[38:39] op_sel_hi:[1,0]
	v_pk_mul_f32 v[28:29], v[28:29], v[38:39] op_sel_hi:[1,0]
	v_pk_mul_f32 v[26:27], v[26:27], v[38:39] op_sel_hi:[1,0]
	v_pk_mul_f32 v[24:25], v[24:25], v[38:39] op_sel_hi:[1,0]
	v_pk_mul_f32 v[22:23], v[22:23], v[38:39] op_sel_hi:[1,0]
	v_pk_mul_f32 v[20:21], v[20:21], v[38:39] op_sel_hi:[1,0]
	v_pk_mul_f32 v[18:19], v[18:19], v[38:39] op_sel_hi:[1,0]
	v_pk_mul_f32 v[16:17], v[16:17], v[38:39] op_sel_hi:[1,0]
	v_pk_mul_f32 v[14:15], v[14:15], v[38:39] op_sel_hi:[1,0]
	v_pk_mul_f32 v[12:13], v[12:13], v[38:39] op_sel_hi:[1,0]
	v_pk_mul_f32 v[10:11], v[10:11], v[38:39] op_sel_hi:[1,0]
	v_pk_mul_f32 v[8:9], v[8:9], v[38:39] op_sel_hi:[1,0]
	v_pk_mul_f32 v[6:7], v[6:7], v[38:39] op_sel_hi:[1,0]
	v_pk_mul_f32 v[4:5], v[4:5], v[38:39] op_sel_hi:[1,0]
	v_pk_mul_f32 v[2:3], v[2:3], v[38:39] op_sel_hi:[1,0]
	v_pk_add_f32 v[96:97], v[96:97], v[36:37] op_sel_hi:[1,0] neg_lo:[0,1] neg_hi:[0,1]
	v_pk_add_f32 v[112:113], v[112:113], v[36:37] op_sel_hi:[1,0] neg_lo:[0,1] neg_hi:[0,1]
	v_sub_f32_e32 v65, v65, v36
	v_sub_f32_e32 v64, v64, v36
	v_sub_f32_e32 v63, v63, v36
	v_sub_f32_e32 v62, v62, v36
	v_sub_f32_e32 v61, v61, v36
	v_sub_f32_e32 v60, v60, v36
	v_sub_f32_e32 v59, v59, v36
	v_sub_f32_e32 v58, v58, v36
	v_sub_f32_e32 v57, v57, v36
	v_sub_f32_e32 v56, v56, v36
	v_sub_f32_e32 v55, v55, v36
	v_sub_f32_e32 v54, v54, v36
	v_sub_f32_e32 v53, v53, v36
	v_sub_f32_e32 v52, v52, v36
	v_sub_f32_e32 v51, v51, v36
	v_sub_f32_e32 v50, v50, v36
	v_sub_f32_e32 v81, v81, v36
	v_sub_f32_e32 v80, v80, v36
	v_sub_f32_e32 v79, v79, v36
	v_sub_f32_e32 v78, v78, v36
	v_sub_f32_e32 v77, v77, v36
	v_sub_f32_e32 v76, v76, v36
	v_sub_f32_e32 v75, v75, v36
	v_sub_f32_e32 v74, v74, v36
	v_sub_f32_e32 v73, v73, v36
	v_sub_f32_e32 v72, v72, v36
	v_sub_f32_e32 v71, v71, v36
	v_sub_f32_e32 v70, v70, v36
	v_sub_f32_e32 v69, v69, v36
	v_sub_f32_e32 v68, v68, v36
	v_sub_f32_e32 v67, v67, v36
	v_sub_f32_e32 v66, v66, v36
	v_mov_b32_e32 v35, v34
	v_mov_b32_e32 v36, v34
	v_mov_b32_e32 v37, v34
	v_mov_b32_e32 v38, v34
	v_mov_b32_e32 v39, v34
	v_mov_b32_e32 v40, v34
	v_mov_b32_e32 v41, v34
	v_mov_b32_e32 v42, v34
	v_mov_b32_e32 v43, v34
	v_mov_b32_e32 v44, v34
	v_mov_b32_e32 v45, v34
	v_mov_b32_e32 v46, v34
	v_mov_b32_e32 v47, v34
	v_mov_b32_e32 v48, v34
	v_mov_b32_e32 v49, v34
